# attn C (diff attn): row-sum l via f32 VALU adds of exp values instead of 4 ones-MFMAs per tile; l transposed through LDS in epilogue
# speedup vs baseline: 1.0080x; 1.0080x over previous
; #define AT_WAITBAR(N) asm volatile("s_waitcnt vmcnt(%0) lgkmcnt(0)\n\ts_barrier" :: "n"(N) : "memory")
; template <int DQK, int DV, bool BAND>
; DI void attn_unit(const AttnArgs& a, LAS unsigned char* lds, int tid) {
;     ...
;             if (t + 1 < t_hi) AT_WAITBAR(NLD); else AT_WAITBAR(0);
;             vnext = vcur == 32768 ? 0 : vcur + 16384; const int vnn = vnext == 32768 ? 0 : vnext + 16384;
;             if (t + 2 < t_hi) AT_DMA(t + 2, vnn);
.LBB0_190:
	s_add_i32 s24, s49, 0x4000
	s_cmpk_lg_u32 s49, 0x8000
	s_cselect_b32 s48, s24, 0
	s_cmp_ge_u32 s47, s69
	s_cbranch_scc1 .LBB0_196
	s_add_i32 s24, s46, 2
	s_lshl_b64 s[40:41], s[24:25], 6
	v_mov_b32_e32 v65, s41
	v_or_b32_e32 v64, s40, v176
	s_andn2_b64 vcc, exec, s[50:51]
	v_lshlrev_b64 v[64:65], 12, v[64:65]
	v_mov_b64_e32 v[66:67], v[180:181]
	s_cbranch_vccnz .LBB0_193
	v_lshl_add_u64 v[66:67], s[52:53], 0, v[64:65]
.LBB0_193:
	s_add_i32 s24, s48, 0x4000
	s_cmpk_lg_u32 s48, 0x8000
	s_cselect_b32 s24, s24, 0
	s_add_i32 s40, s24, 0
	s_add_i32 s41, s40, s83
	s_mov_b32 s56, m0
	s_mov_b32 m0, s41
	s_nop 0
	global_load_lds_dwordx4 v[66:67], off
	s_mov_b32 m0, s56
	s_and_b64 vcc, exec, s[44:45]
	v_mov_b64_e32 v[66:67], v[178:179]
	s_cbranch_vccnz .LBB0_195
	v_lshl_add_u64 v[66:67], s[54:55], 0, v[64:65]
.LBB0_195:
	s_add_i32 s40, s40, s88
	s_mov_b32 s41, m0
	s_mov_b32 m0, s40
	s_nop 0
	global_load_lds_dwordx4 v[66:67], off
	s_mov_b32 m0, s41
	s_add_i32 s24, s89, s24
	s_mov_b32 s40, m0
	s_mov_b32 m0, s24
	s_nop 0
	global_load_lds_dwordx4 v[174:175], off
	s_mov_b32 m0, s40
; template <int DQK, int DV, bool BAND>
; DI void attn_unit(const AttnArgs& a, LAS unsigned char* lds, int tid) {
;     ...
;             const LAS unsigned char* kb = lds + KBUF + vcur + hi * 1024 + r32 * 16;
; #pragma unroll
;             for (int dg = 0; dg < ND0; dg += KG) {
;                 bf16x8 kf0[KG], kf1[KG];
; #pragma unroll
;                 for (int j = 0; j < KG; ++j) if (dg + j < ND0) { kf0[j] = *(const LAS bf16x8*)(kb + (dg + j) * 2048); kf1[j] = *(const LAS bf16x8*)(kb + (dg + j) * 2048 + 512); }
;                 __builtin_amdgcn_sched_barrier(0);
; #pragma unroll
;                 for (int j = 0; j < KG; ++j) if (dg + j < ND0) {
;                     if (dg + j == 0) { p0 = MFMA32(kf0[j], qf[0], negm); p1 = MFMA32(kf1[j], qf[0], negm); }
;                     else { p0 = MFMA32(kf0[j], qf[dg + j], p0); p1 = MFMA32(kf1[j], qf[dg + j], p1); }
;                 }
;             }
;             s16x4 vlo[8], vhi[8];
;             if (VPRE) { const LAS unsigned char* vp_ = lds + VBUF + vcur + ((lane >> 4) & 1) * 32 + (lane & 3) * 8 + (4 * hi + ((lane & 15) >> 2)) * 64;
; #pragma unroll
;               for (int d = 0; d < 2; ++d)
; #pragma unroll
;                   for (int ks = 0; ks < 4; ++ks) { vlo[d * 4 + ks] = vtr(vp_ + d * 4096 + ks * 1024); vhi[d * 4 + ks] = vtr(vp_ + d * 4096 + ks * 1024 + 512); } }
;             __builtin_amdgcn_sched_barrier(0);
;             if (BAND) { const int qi = qw + r32; const int kb0 = 64 * t + 4 * hi;
; #pragma unroll
;                 for (int r = 0; r < 16; ++r) { const int kv = kb0 + (r & 3) + 8 * (r >> 2); int d = qi - kv; d = d < 0 ? -d : d; if (d > 64) p0[r] = -1e30f; int d2 = qi - kv - 32; d2 = d2 < 0 ? -d2 : d2; if (d2 > 64) p1[r] = -1e30f; } }
;             if (!a.nomax) {
;             float mx = fmaxf(p0[0], p1[0]);
; #pragma unroll
;             for (int r = 1; r < 16; ++r) mx = fmaxf(fmaxf(mx, p0[r]), p1[r]);
;             { const unsigned mu = __float_as_uint(mx); auto rr = __builtin_amdgcn_permlane32_swap(mu, mu, false, false); mx = fmaxf(__uint_as_float(rr[0]), __uint_as_float(rr[1])); }
;             if (first || __any(mx > 8.0f)) {
;                 const float delta = first ? fmaxf(mx, -1e4f) : fmaxf(mx, 0.f);
;                 m_run += delta;
; #pragma unroll
;                 for (int r = 0; r < 16; ++r) { p0[r] -= delta; p1[r] -= delta; negm[r] = -m_run; }
;                 if (!first) {
.LBB0_196:
	v_add_u32_e32 v148, s49, v183
	ds_read_b128 v[80:83], v148
	ds_read_b128 v[120:123], v148 offset:512
	ds_read_b128 v[124:127], v148 offset:2048
	ds_read_b128 v[128:131], v148 offset:2560
	ds_read_b128 v[132:135], v148 offset:4096
	ds_read_b128 v[136:139], v148 offset:4608
	ds_read_b128 v[140:143], v148 offset:6144
	ds_read_b128 v[144:147], v148 offset:6656
	s_waitcnt lgkmcnt(7)
	v_mfma_f32_32x32x16_bf16 v[64:79], v[80:83], v[96:99], v[48:63]
	v_mov_b64_e32 v[94:95], v[62:63]
	v_mov_b64_e32 v[92:93], v[60:61]
	v_mov_b64_e32 v[90:91], v[58:59]
	v_mov_b64_e32 v[88:89], v[56:57]
	v_mov_b64_e32 v[86:87], v[54:55]
	v_mov_b64_e32 v[84:85], v[52:53]
	v_mov_b64_e32 v[82:83], v[50:51]
	v_mov_b64_e32 v[80:81], v[48:49]
	s_waitcnt lgkmcnt(5)
	v_mfma_f32_32x32x16_bf16 v[64:79], v[124:127], v[100:103], v[64:79]
	v_mfma_f32_32x32x16_bf16 v[80:95], v[120:123], v[96:99], v[80:95]
	s_waitcnt lgkmcnt(4)
	v_mfma_f32_32x32x16_bf16 v[80:95], v[128:131], v[100:103], v[80:95]
	s_waitcnt lgkmcnt(3)
	v_mfma_f32_32x32x16_bf16 v[64:79], v[132:135], v[104:107], v[64:79]
	ds_read_b128 v[120:123], v148 offset:8192
	ds_read_b128 v[124:127], v148 offset:8704
	ds_read_b128 v[128:131], v148 offset:10240
	ds_read_b128 v[132:135], v148 offset:10752
	s_waitcnt lgkmcnt(6)
	v_mfma_f32_32x32x16_bf16 v[80:95], v[136:139], v[104:107], v[80:95]
	s_waitcnt lgkmcnt(5)
	v_mfma_f32_32x32x16_bf16 v[64:79], v[140:143], v[108:111], v[64:79]
	s_waitcnt lgkmcnt(4)
	v_mfma_f32_32x32x16_bf16 v[80:95], v[144:147], v[108:111], v[80:95]
	s_waitcnt lgkmcnt(3)
	v_mfma_f32_32x32x16_bf16 v[64:79], v[120:123], v[112:115], v[64:79]
	s_waitcnt lgkmcnt(2)
	v_mfma_f32_32x32x16_bf16 v[80:95], v[124:127], v[112:115], v[80:95]
	v_add_u32_e32 v126, s49, v185
	s_waitcnt lgkmcnt(1)
	v_mfma_f32_32x32x16_bf16 v[64:79], v[128:131], v[116:119], v[64:79]
	s_waitcnt lgkmcnt(0)
	v_mfma_f32_32x32x16_bf16 v[80:95], v[132:135], v[116:119], v[80:95]
	ds_read_b64_tr_b16 v[148:149], v126 offset:49152
	ds_read_b64_tr_b16 v[150:151], v126 offset:49664
	ds_read_b64_tr_b16 v[140:141], v126 offset:50176
	ds_read_b64_tr_b16 v[142:143], v126 offset:50688
	ds_read_b64_tr_b16 v[132:133], v126 offset:51200
	ds_read_b64_tr_b16 v[134:135], v126 offset:51712
	ds_read_b64_tr_b16 v[120:121], v126 offset:52224
	ds_read_b64_tr_b16 v[122:123], v126 offset:52736
	ds_read_b64_tr_b16 v[144:145], v126 offset:53248
	ds_read_b64_tr_b16 v[146:147], v126 offset:53760
	ds_read_b64_tr_b16 v[136:137], v126 offset:54272
	ds_read_b64_tr_b16 v[138:139], v126 offset:54784
	ds_read_b64_tr_b16 v[128:129], v126 offset:55296
	ds_read_b64_tr_b16 v[130:131], v126 offset:55808
	ds_read_b64_tr_b16 v[124:125], v126 offset:56320
	ds_read_b64_tr_b16 v[126:127], v126 offset:56832
	v_max_f32_e32 v194, v80, v80
	v_max_f32_e32 v201, v64, v64
	v_max_f32_e32 v194, v201, v194
	v_max3_f32 v194, v194, v65, v81
	v_max3_f32 v194, v194, v66, v82
	v_max3_f32 v194, v194, v67, v83
	v_max3_f32 v194, v194, v68, v84
	v_max3_f32 v194, v194, v69, v85
	v_max3_f32 v194, v194, v70, v86
	v_max3_f32 v194, v194, v71, v87
	v_max3_f32 v194, v194, v72, v88
	v_max3_f32 v194, v194, v73, v89
	v_max3_f32 v194, v194, v74, v90
	v_max3_f32 v194, v194, v75, v91
	v_max3_f32 v194, v194, v76, v92
	v_max3_f32 v194, v194, v77, v93
	v_max3_f32 v194, v194, v78, v94
	v_max3_f32 v194, v194, v79, v95
	v_mov_b32_e32 v201, v194
	s_nop 1
	v_permlane32_swap_b32_e32 v194, v201
	v_max_f32_e32 v201, v201, v201
	v_max_f32_e32 v194, v194, v194
	v_max_f32_e32 v194, v194, v201
	v_cmp_lt_f32_e32 vcc, s90, v194
	s_cbranch_vccz .LBB0_200
	v_max_f32_e32 v48, v194, v194
	v_max_f32_e32 v48, 0, v48
	s_and_saveexec_b64 s[40:41], s[0:1]
	v_exp_f32_e64 v49, -v48
	ds_write_b32 v171, v49
	s_or_b64 exec, exec, s[40:41]
	v_add_f32_e32 v200, v200, v48
	v_sub_f32_e32 v64, v64, v48
	v_sub_f32_e32 v65, v65, v48
	v_sub_f32_e32 v66, v66, v48
	v_sub_f32_e32 v67, v67, v48
	v_sub_f32_e32 v68, v68, v48
	v_sub_f32_e32 v69, v69, v48
	v_sub_f32_e32 v70, v70, v48
	v_sub_f32_e32 v71, v71, v48
	v_sub_f32_e32 v72, v72, v48
	v_sub_f32_e32 v73, v73, v48
	v_sub_f32_e32 v74, v74, v48
	v_sub_f32_e32 v75, v75, v48
	v_sub_f32_e32 v76, v76, v48
	v_sub_f32_e32 v77, v77, v48
	v_sub_f32_e32 v78, v78, v48
	v_sub_f32_e32 v79, v79, v48
	v_sub_f32_e32 v80, v80, v48
	v_sub_f32_e32 v81, v81, v48
	v_sub_f32_e32 v82, v82, v48
	v_sub_f32_e32 v83, v83, v48
	v_sub_f32_e32 v84, v84, v48
	v_sub_f32_e32 v85, v85, v48
	v_sub_f32_e32 v86, v86, v48
	v_sub_f32_e32 v87, v87, v48
	v_sub_f32_e32 v88, v88, v48
	v_sub_f32_e32 v89, v89, v48
	v_sub_f32_e32 v90, v90, v48
	v_sub_f32_e32 v91, v91, v48
	v_sub_f32_e32 v92, v92, v48
	v_sub_f32_e32 v93, v93, v48
	v_sub_f32_e32 v94, v94, v48
	v_sub_f32_e32 v95, v95, v48
	ds_read_b128 v[48:51], v173
	ds_read_b128 v[52:55], v173 offset:32
	ds_read_b128 v[56:59], v173 offset:64
	ds_read_b128 v[204:207], v173 offset:96
	v_xor_b32_e32 v63, 0x80000000, v200
	s_waitcnt lgkmcnt(3)
	v_pk_mul_f32 v[18:19], v[18:19], v[50:51]
	s_waitcnt lgkmcnt(2)
	v_pk_mul_f32 v[22:23], v[22:23], v[54:55]
	s_waitcnt lgkmcnt(1)
	v_pk_mul_f32 v[26:27], v[26:27], v[58:59]
	s_waitcnt lgkmcnt(0)
	v_pk_mul_f32 v[30:31], v[30:31], v[206:207]
	v_pk_mul_f32 v[14:15], v[14:15], v[206:207]
	v_pk_mul_f32 v[10:11], v[10:11], v[58:59]
	v_pk_mul_f32 v[6:7], v[6:7], v[54:55]
	v_pk_mul_f32 v[2:3], v[2:3], v[50:51]
	v_pk_mul_f32 v[28:29], v[28:29], v[204:205]
	v_pk_mul_f32 v[24:25], v[24:25], v[56:57]
	v_pk_mul_f32 v[20:21], v[20:21], v[52:53]
	v_pk_mul_f32 v[16:17], v[16:17], v[48:49]
	v_pk_mul_f32 v[12:13], v[12:13], v[204:205]
	v_pk_mul_f32 v[8:9], v[8:9], v[56:57]
	v_pk_mul_f32 v[4:5], v[4:5], v[52:53]
	v_pk_mul_f32 v[0:1], v[0:1], v[48:49]
	v_pk_mul_f32 v[46:47], v[46:47], v[206:207]
	v_pk_mul_f32 v[42:43], v[42:43], v[58:59]
	v_pk_mul_f32 v[38:39], v[38:39], v[54:55]
	v_pk_mul_f32 v[34:35], v[34:35], v[50:51]
	v_pk_mul_f32 v[44:45], v[44:45], v[204:205]
	v_pk_mul_f32 v[40:41], v[40:41], v[56:57]
	v_pk_mul_f32 v[36:37], v[36:37], v[52:53]
	v_pk_mul_f32 v[32:33], v[32:33], v[48:49]
	v_mov_b32_e32 v62, v63
	v_mov_b32_e32 v61, v63
	v_mov_b32_e32 v60, v63
	v_mov_b32_e32 v59, v63
	v_mov_b32_e32 v58, v63
	v_mov_b32_e32 v57, v63
	v_mov_b32_e32 v56, v63
	v_mov_b32_e32 v55, v63
	v_mov_b32_e32 v54, v63
	v_mov_b32_e32 v53, v63
	v_mov_b32_e32 v52, v63
	v_mov_b32_e32 v51, v63
	v_mov_b32_e32 v50, v63
	v_mov_b32_e32 v49, v63
	v_mov_b32_e32 v48, v63

; #define LAS __attribute__((address_space(3)))
; #define GASA __attribute__((address_space(1)))
; DI unsigned pk2(float lo, float hi) { f32x2 v = {lo, hi}; bf16x2_t b = __builtin_convertvector(v, bf16x2_t); return __builtin_bit_cast(unsigned, b); }
; template <int DQK, int DV, bool BAND>
; DI void attn_unit(const AttnArgs& a, LAS unsigned char* lds, int tid) {
;     ...
;     asm volatile("s_waitcnt lgkmcnt(0)\n\ts_barrier" ::: "memory");
;     __builtin_amdgcn_s_setprio(0);
;     { if (a.lse != nullptr) {
;           if (hi == 0) scr[r32] = m_run;
; #pragma unroll
;           for (int g = 0; g < 4; ++g) { const f32x4 mr = *(const LAS f32x4*)(scr + 8 * g + 4 * hi);
; #pragma unroll
;               for (int e = 0; e < 4; ++e) if (r32 == 0) ((GASA float*)a.lse)[(long)(wid * 32 + 8 * g + 4 * hi + e) * a.lses] = mr[e] + __builtin_amdgcn_logf(lacc[4 * g + e]); } }
;       LAS bf16_t* stg = (LAS bf16_t*)(lds + wid * 8192);
; #pragma unroll
;       for (int g = 0; g < 4; ++g) {
; #pragma unroll
;           for (int e = 0; e < 4; ++e) { const int orow = 8 * g + 4 * hi + e; const float rr = __builtin_amdgcn_rcpf(lacc[4 * g + e]);
; #pragma unroll
;               for (int d = 0; d < NDB; ++d) stg[orow * DV + d * 32 + r32] = (bf16_t)(pk2(o[d][4 * g + e] * rr, 0.f) & 0xffffu); } }
.LBB0_207:
	s_lshl_b64 s[26:27], s[42:43], 12
	s_add_u32 s24, s12, s26
	s_addc_u32 s34, s13, s27
	s_lshl_b32 s26, s18, 7
	s_ashr_i32 s27, s26, 31
	s_waitcnt lgkmcnt(0)
	s_barrier
	v_add_f32_e32 v64, v64, v65
	s_nop 0
	v_mov_b32_e32 v65, v64
	s_nop 1
	v_permlane32_swap_b32_e32 v64, v65
	s_nop 1
	v_add_f32_e32 v64, v64, v65
	ds_write_b32 v185, v64
	s_waitcnt lgkmcnt(0)
	ds_read_b128 v[64:67], v187
	ds_read_b128 v[68:71], v187 offset:32
	ds_read_b128 v[72:75], v187 offset:64
	ds_read_b128 v[76:79], v187 offset:96
	s_waitcnt lgkmcnt(0)
	s_lshl_b64 s[26:27], s[26:27], 1
	s_add_u32 s40, s24, s26
	s_addc_u32 s41, s34, s27
	s_setprio 0
	s_nop 1
	v_rcp_f32_e32 v64, v64
	s_lshl_b32 s18, s19, 13
	s_add_i32 s18, s18, 0
	v_lshlrev_b32_e32 v80, 1, v196
	v_mul_f32_e32 v0, v0, v64
	v_add3_u32 v80, s18, v80, v204
	v_cvt_pk_bf16_f32 v0, v0, s0
	ds_write_b16 v80, v0
	v_mul_f32_e32 v0, v48, v64
	v_cvt_pk_bf16_f32 v0, v0, s0
	ds_write_b16 v80, v0 offset:64
	v_mul_f32_e32 v0, v32, v64
	v_cvt_pk_bf16_f32 v0, v0, s0
	ds_write_b16 v80, v0 offset:128
	v_rcp_f32_e32 v0, v65
	v_mul_f32_e32 v16, v16, v64
	v_cvt_pk_bf16_f32 v16, v16, s0
	ds_write_b16 v80, v16 offset:192
	v_mul_f32_e32 v1, v1, v0
	v_cvt_pk_bf16_f32 v1, v1, s0
	ds_write_b16 v80, v1 offset:256
	v_mul_f32_e32 v1, v49, v0
	v_cvt_pk_bf16_f32 v1, v1, s0
	ds_write_b16 v80, v1 offset:320
	v_mul_f32_e32 v1, v33, v0
	v_cvt_pk_bf16_f32 v1, v1, s0
	ds_write_b16 v80, v1 offset:384
	v_rcp_f32_e32 v1, v66
	v_mul_f32_e32 v0, v17, v0
	v_cvt_pk_bf16_f32 v0, v0, s0
	ds_write_b16 v80, v0 offset:448
	v_mul_f32_e32 v0, v2, v1
	v_cvt_pk_bf16_f32 v0, v0, s0
	ds_write_b16 v80, v0 offset:512
	v_mul_f32_e32 v0, v50, v1
	v_cvt_pk_bf16_f32 v0, v0, s0
	ds_write_b16 v80, v0 offset:576
	v_mul_f32_e32 v0, v34, v1
	v_cvt_pk_bf16_f32 v0, v0, s0
	ds_write_b16 v80, v0 offset:640
	v_rcp_f32_e32 v0, v67
	v_mul_f32_e32 v1, v18, v1
	v_cvt_pk_bf16_f32 v1, v1, s0
	ds_write_b16 v80, v1 offset:704
	v_mul_f32_e32 v1, v3, v0
	v_cvt_pk_bf16_f32 v1, v1, s0
	ds_write_b16 v80, v1 offset:768
	v_mul_f32_e32 v1, v51, v0
	v_cvt_pk_bf16_f32 v1, v1, s0
	ds_write_b16 v80, v1 offset:832
	v_mul_f32_e32 v1, v35, v0
	v_cvt_pk_bf16_f32 v1, v1, s0
	ds_write_b16 v80, v1 offset:896
	v_rcp_f32_e32 v1, v68
	v_mul_f32_e32 v0, v19, v0
	v_cvt_pk_bf16_f32 v0, v0, s0
	ds_write_b16 v80, v0 offset:960
	v_mul_f32_e32 v0, v4, v1
	v_cvt_pk_bf16_f32 v0, v0, s0
	ds_write_b16 v80, v0 offset:2048
	v_mul_f32_e32 v0, v52, v1
	v_cvt_pk_bf16_f32 v0, v0, s0
	ds_write_b16 v80, v0 offset:2112
	v_mul_f32_e32 v0, v36, v1
	v_cvt_pk_bf16_f32 v0, v0, s0
	ds_write_b16 v80, v0 offset:2176
	v_rcp_f32_e32 v0, v69
	v_mul_f32_e32 v1, v20, v1
	v_cvt_pk_bf16_f32 v1, v1, s0
	ds_write_b16 v80, v1 offset:2240
	v_mul_f32_e32 v1, v5, v0
	v_cvt_pk_bf16_f32 v1, v1, s0
	ds_write_b16 v80, v1 offset:2304
	v_mul_f32_e32 v1, v53, v0
	v_cvt_pk_bf16_f32 v1, v1, s0
	ds_write_b16 v80, v1 offset:2368
	v_mul_f32_e32 v1, v37, v0
	v_cvt_pk_bf16_f32 v1, v1, s0
	ds_write_b16 v80, v1 offset:2432
	v_rcp_f32_e32 v1, v70
	v_mul_f32_e32 v0, v21, v0
	v_cvt_pk_bf16_f32 v0, v0, s0
	ds_write_b16 v80, v0 offset:2496
	v_mul_f32_e32 v0, v6, v1
	v_cvt_pk_bf16_f32 v0, v0, s0
	ds_write_b16 v80, v0 offset:2560
	v_mul_f32_e32 v0, v54, v1
	v_cvt_pk_bf16_f32 v0, v0, s0
	ds_write_b16 v80, v0 offset:2624
	v_mul_f32_e32 v0, v38, v1
	v_cvt_pk_bf16_f32 v0, v0, s0
	ds_write_b16 v80, v0 offset:2688
	v_rcp_f32_e32 v0, v71
	v_mul_f32_e32 v1, v22, v1
	v_cvt_pk_bf16_f32 v1, v1, s0
	ds_write_b16 v80, v1 offset:2752
	v_mul_f32_e32 v1, v7, v0
	v_cvt_pk_bf16_f32 v1, v1, s0
	ds_write_b16 v80, v1 offset:2816
	v_mul_f32_e32 v1, v55, v0
	v_cvt_pk_bf16_f32 v1, v1, s0
	ds_write_b16 v80, v1 offset:2880
	v_mul_f32_e32 v1, v39, v0
	v_cvt_pk_bf16_f32 v1, v1, s0
	ds_write_b16 v80, v1 offset:2944
	v_rcp_f32_e32 v1, v72
	v_mul_f32_e32 v0, v23, v0
	v_cvt_pk_bf16_f32 v0, v0, s0
	ds_write_b16 v80, v0 offset:3008
	v_mul_f32_e32 v0, v8, v1
	v_cvt_pk_bf16_f32 v0, v0, s0
	ds_write_b16 v80, v0 offset:4096
	v_mul_f32_e32 v0, v56, v1
	v_cvt_pk_bf16_f32 v0, v0, s0
	ds_write_b16 v80, v0 offset:4160
	v_mul_f32_e32 v0, v40, v1
	v_cvt_pk_bf16_f32 v0, v0, s0
	ds_write_b16 v80, v0 offset:4224
	v_rcp_f32_e32 v0, v73
	v_mul_f32_e32 v1, v24, v1
	v_cvt_pk_bf16_f32 v1, v1, s0
	ds_write_b16 v80, v1 offset:4288
	v_mul_f32_e32 v1, v9, v0
	v_cvt_pk_bf16_f32 v1, v1, s0
	ds_write_b16 v80, v1 offset:4352
	v_mul_f32_e32 v1, v57, v0
	v_cvt_pk_bf16_f32 v1, v1, s0
	ds_write_b16 v80, v1 offset:4416
	v_mul_f32_e32 v1, v41, v0
	v_cvt_pk_bf16_f32 v1, v1, s0
	ds_write_b16 v80, v1 offset:4480
	v_rcp_f32_e32 v1, v74
	v_mul_f32_e32 v0, v25, v0
	v_cvt_pk_bf16_f32 v0, v0, s0
	ds_write_b16 v80, v0 offset:4544
	v_mul_f32_e32 v0, v10, v1
	v_cvt_pk_bf16_f32 v0, v0, s0
	ds_write_b16 v80, v0 offset:4608
	v_mul_f32_e32 v0, v58, v1
	v_cvt_pk_bf16_f32 v0, v0, s0
; #define LAS __attribute__((address_space(3)))
; #define GASA __attribute__((address_space(1)))
; DI unsigned pk2(float lo, float hi) { f32x2 v = {lo, hi}; bf16x2_t b = __builtin_convertvector(v, bf16x2_t); return __builtin_bit_cast(unsigned, b); }
; template <int DQK, int DV, bool BAND>
; DI void attn_unit(const AttnArgs& a, LAS unsigned char* lds, int tid) {
;     ...
;       for (int g = 0; g < 4; ++g) {
; #pragma unroll
;           for (int e = 0; e < 4; ++e) { const int orow = 8 * g + 4 * hi + e; const float rr = __builtin_amdgcn_rcpf(lacc[4 * g + e]);
; #pragma unroll
;               for (int d = 0; d < NDB; ++d) stg[orow * DV + d * 32 + r32] = (bf16_t)(pk2(o[d][4 * g + e] * rr, 0.f) & 0xffffu); } }
;       constexpr int CPR = DV / 8, RPI = 64 / CPR;
; #pragma unroll
;       for (int i = 0; i < 32 / RPI; ++i) { const int row = i * RPI + lane / CPR, ch = lane % CPR;
;           const u32x4 v = *(const LAS u32x4*)(stg + row * DV + ch * 8); *(GASA u32x4*)((GASA bf16_t*)a.o + (long)(wid * 32 + row) * a.os + ch * 8) = v; }
	ds_write_b16 v80, v0 offset:4672
	v_mul_f32_e32 v0, v42, v1
	v_cvt_pk_bf16_f32 v0, v0, s0
	ds_write_b16 v80, v0 offset:4736
	v_rcp_f32_e32 v0, v75
	v_mul_f32_e32 v1, v26, v1
	v_cvt_pk_bf16_f32 v1, v1, s0
	ds_write_b16 v80, v1 offset:4800
	v_mul_f32_e32 v1, v11, v0
	v_cvt_pk_bf16_f32 v1, v1, s0
	ds_write_b16 v80, v1 offset:4864
	v_mul_f32_e32 v1, v59, v0
	v_cvt_pk_bf16_f32 v1, v1, s0
	ds_write_b16 v80, v1 offset:4928
	v_mul_f32_e32 v1, v43, v0
	v_cvt_pk_bf16_f32 v1, v1, s0
	ds_write_b16 v80, v1 offset:4992
	v_rcp_f32_e32 v1, v76
	v_mul_f32_e32 v0, v27, v0
	v_cvt_pk_bf16_f32 v0, v0, s0
	ds_write_b16 v80, v0 offset:5056
	v_mul_f32_e32 v0, v12, v1
	v_cvt_pk_bf16_f32 v0, v0, s0
	ds_write_b16 v80, v0 offset:6144
	v_mul_f32_e32 v0, v60, v1
	v_cvt_pk_bf16_f32 v0, v0, s0
	ds_write_b16 v80, v0 offset:6208
	v_mul_f32_e32 v0, v44, v1
	v_cvt_pk_bf16_f32 v0, v0, s0
	ds_write_b16 v80, v0 offset:6272
	v_rcp_f32_e32 v0, v77
	v_mul_f32_e32 v1, v28, v1
	v_cvt_pk_bf16_f32 v1, v1, s0
	ds_write_b16 v80, v1 offset:6336
	v_mul_f32_e32 v1, v13, v0
	v_cvt_pk_bf16_f32 v1, v1, s0
	ds_write_b16 v80, v1 offset:6400
	v_mul_f32_e32 v1, v61, v0
	v_cvt_pk_bf16_f32 v1, v1, s0
	ds_write_b16 v80, v1 offset:6464
	v_mul_f32_e32 v1, v45, v0
	v_cvt_pk_bf16_f32 v1, v1, s0
	ds_write_b16 v80, v1 offset:6528
	v_rcp_f32_e32 v1, v78
	v_mul_f32_e32 v0, v29, v0
	v_cvt_pk_bf16_f32 v0, v0, s0
	ds_write_b16 v80, v0 offset:6592
	v_mul_f32_e32 v0, v14, v1
	v_cvt_pk_bf16_f32 v0, v0, s0
	ds_write_b16 v80, v0 offset:6656
	v_mul_f32_e32 v0, v62, v1
	v_cvt_pk_bf16_f32 v0, v0, s0
	ds_write_b16 v80, v0 offset:6720
	v_mul_f32_e32 v0, v46, v1
	v_cvt_pk_bf16_f32 v0, v0, s0
	ds_write_b16 v80, v0 offset:6784
	v_rcp_f32_e32 v0, v79
	v_mul_f32_e32 v1, v30, v1
	v_cvt_pk_bf16_f32 v1, v1, s0
	ds_write_b16 v80, v1 offset:6848
	v_mul_f32_e32 v1, v15, v0
	v_cvt_pk_bf16_f32 v1, v1, s0
	ds_write_b16 v80, v1 offset:6912
	v_mul_f32_e32 v1, v63, v0
	v_cvt_pk_bf16_f32 v1, v1, s0
	ds_write_b16 v80, v1 offset:6976
	v_mul_f32_e32 v1, v47, v0
	v_mul_f32_e32 v0, v31, v0
	v_cvt_pk_bf16_f32 v0, v0, s0
	v_add_u32_e32 v10, s18, v188
	v_cvt_pk_bf16_f32 v1, v1, s0
	ds_write_b16 v80, v0 offset:7104
	v_add_u32_e32 v0, v10, v209
	ds_write_b16 v80, v1 offset:7040
	ds_read_b128 v[0:3], v0
	v_or_b32_e32 v4, s17, v208
	v_ashrrev_i32_e32 v5, 31, v4
	v_lshlrev_b64 v[4:5], 12, v[4:5]
	v_lshl_add_u64 v[4:5], s[40:41], 0, v[4:5]
	v_mov_b32_e32 v189, v195
	v_lshl_add_u64 v[8:9], v[4:5], 0, v[188:189]
	v_add_u32_e32 v4, v10, v211
	ds_read_b128 v[4:7], v4
	s_waitcnt lgkmcnt(1)
	global_store_dwordx4 v[8:9], v[0:3], off
	s_add_i32 s16, s16, s58
	s_nop 0
	v_or_b32_e32 v0, s17, v210
	v_ashrrev_i32_e32 v1, 31, v0
	v_lshlrev_b64 v[0:1], 12, v[0:1]
	v_lshl_add_u64 v[0:1], s[40:41], 0, v[0:1]
	v_lshl_add_u64 v[0:1], v[0:1], 0, v[188:189]
	s_waitcnt lgkmcnt(0)
	global_store_dwordx4 v[0:1], v[4:7], off
	v_add_u32_e32 v0, v10, v213
	ds_read_b128 v[0:3], v0
	v_or_b32_e32 v4, s17, v212
	v_ashrrev_i32_e32 v5, 31, v4
	v_lshlrev_b64 v[4:5], 12, v[4:5]
	v_lshl_add_u64 v[4:5], s[40:41], 0, v[4:5]
	v_lshl_add_u64 v[8:9], v[4:5], 0, v[188:189]
	v_add_u32_e32 v4, v10, v215
	ds_read_b128 v[4:7], v4
	s_waitcnt lgkmcnt(1)
	global_store_dwordx4 v[8:9], v[0:3], off
	s_nop 1
	v_or_b32_e32 v0, s17, v214
	v_ashrrev_i32_e32 v1, 31, v0
	v_lshlrev_b64 v[0:1], 12, v[0:1]
	v_lshl_add_u64 v[0:1], s[40:41], 0, v[0:1]
	v_lshl_add_u64 v[0:1], v[0:1], 0, v[188:189]
	s_waitcnt lgkmcnt(0)
	global_store_dwordx4 v[0:1], v[4:7], off
	v_add_u32_e32 v0, v10, v217
	ds_read_b128 v[0:3], v0
	v_or_b32_e32 v4, s17, v216
	v_ashrrev_i32_e32 v5, 31, v4
	v_lshlrev_b64 v[4:5], 12, v[4:5]
	v_lshl_add_u64 v[4:5], s[40:41], 0, v[4:5]
	v_lshl_add_u64 v[8:9], v[4:5], 0, v[188:189]
	v_add_u32_e32 v4, v10, v219
	ds_read_b128 v[4:7], v4
	s_waitcnt lgkmcnt(1)
	global_store_dwordx4 v[8:9], v[0:3], off
	s_nop 1
	v_or_b32_e32 v0, s17, v218
	v_ashrrev_i32_e32 v1, 31, v0
	v_lshlrev_b64 v[0:1], 12, v[0:1]
	v_lshl_add_u64 v[0:1], s[40:41], 0, v[0:1]
	v_lshl_add_u64 v[0:1], v[0:1], 0, v[188:189]
	s_waitcnt lgkmcnt(0)
	global_store_dwordx4 v[0:1], v[4:7], off
	v_add_u32_e32 v0, v10, v221
	ds_read_b128 v[0:3], v0
	v_or_b32_e32 v4, s17, v220
	v_ashrrev_i32_e32 v5, 31, v4
	v_lshlrev_b64 v[4:5], 12, v[4:5]
	v_lshl_add_u64 v[4:5], s[40:41], 0, v[4:5]
	v_lshl_add_u64 v[8:9], v[4:5], 0, v[188:189]
	v_add_u32_e32 v4, v10, v223
	ds_read_b128 v[4:7], v4
	s_waitcnt lgkmcnt(1)
	global_store_dwordx4 v[8:9], v[0:3], off
	s_nop 1
	v_or_b32_e32 v0, s17, v222
	v_ashrrev_i32_e32 v1, 31, v0
	v_lshlrev_b64 v[0:1], 12, v[0:1]
	v_lshl_add_u64 v[0:1], s[40:41], 0, v[0:1]
	v_readlane_b32 s17, v254, 23
	v_lshl_add_u64 v[0:1], v[0:1], 0, v[188:189]
	s_cmp_ge_i32 s16, s17
	s_waitcnt lgkmcnt(0)
	global_store_dwordx4 v[0:1], v[4:7], off
	s_barrier
	s_cbranch_scc1 .LBB0_230

; #define LAS __attribute__((address_space(3)))
; template <int DQK, int DV, bool BAND>
; DI void attn_unit(const AttnArgs& a, LAS unsigned char* lds, int tid) {
;     ...
;             if (t + 1 < t_hi) AT_WAITBAR(NLD); else AT_WAITBAR(0);
;             vnext = vcur == 32768 ? 0 : vcur + 16384; const int vnn = vnext == 32768 ? 0 : vnext + 16384;
;             if (t + 2 < t_hi) AT_DMA(t + 2, vnn);
;         }
;         bool active = true;
;         if (BAND) active = (64 * t + 63 >= qw - 64) && (64 * t <= qw + 95);
;         if (active) {
;             f32x16 p0, p1;
;             const LAS unsigned char* kb = lds + KBUF + vcur + hi * 1024 + r32 * 16;
; #pragma unroll
;             for (int dg = 0; dg < ND0; dg += KG) {
;                 bf16x8 kf0[KG], kf1[KG];
; #pragma unroll
;                 for (int j = 0; j < KG; ++j) if (dg + j < ND0) { kf0[j] = *(const LAS bf16x8*)(kb + (dg + j) * 2048); kf1[j] = *(const LAS bf16x8*)(kb + (dg + j) * 2048 + 512); }
;                 __builtin_amdgcn_sched_barrier(0);
; #pragma unroll
;                 for (int j = 0; j < KG; ++j) if (dg + j < ND0) {
;                     if (dg + j == 0) { p0 = MFMA32(kf0[j], qf[0], negm); p1 = MFMA32(kf1[j], qf[0], negm); }
;                     else { p0 = MFMA32(kf0[j], qf[dg + j], p0); p1 = MFMA32(kf1[j], qf[dg + j], p1); }
;                 }
;             }
;             s16x4 vlo[8], vhi[8];
;             if (VPRE) { const LAS unsigned char* vp_ = lds + VBUF + vcur + ((lane >> 4) & 1) * 32 + (lane & 3) * 8 + (4 * hi + ((lane & 15) >> 2)) * 64;
; #pragma unroll
;               for (int d = 0; d < 2; ++d)
; #pragma unroll
;                   for (int ks = 0; ks < 4; ++ks) { vlo[d * 4 + ks] = vtr(vp_ + d * 4096 + ks * 1024); vhi[d * 4 + ks] = vtr(vp_ + d * 4096 + ks * 1024 + 512); } }
;             __builtin_amdgcn_sched_barrier(0);
;             if (BAND) { const int qi = qw + r32; const int kb0 = 64 * t + 4 * hi;
; #pragma unroll
;                 for (int r = 0; r < 16; ++r) { const int kv = kb0 + (r & 3) + 8 * (r >> 2); int d = qi - kv; d = d < 0 ? -d : d; if (d > 64) p0[r] = -1e30f; int d2 = qi - kv - 32; d2 = d2 < 0 ? -d2 : d2; if (d2 > 64) p1[r] = -1e30f; } }
;             if (!a.nomax) {
;             float mx = fmaxf(p0[0], p1[0]);
; #pragma unroll
;             for (int r = 1; r < 16; ++r) mx = fmaxf(fmaxf(mx, p0[r]), p1[r]);
.LBB0_214:
	s_add_i32 s35, s48, 0x4000
	s_cmpk_lg_u32 s48, 0x8000
	s_cselect_b32 s35, s35, 0
	s_cmp_ge_u32 s34, s69
	s_cbranch_scc1 .LBB0_216
	s_add_i32 s46, s35, 0x4000
	s_cmpk_lg_u32 s35, 0x8000
	s_cselect_b32 s46, s46, 0
	s_add_i32 s47, s26, s46
	s_add_i32 s46, s46, 0
	s_mov_b32 s49, m0
	s_mov_b32 m0, s47
	s_nop 0
	global_load_lds_dwordx4 v[200:201], off
	s_mov_b32 m0, s49
	s_add_i32 s46, s46, 0xc000
	s_add_i32 s47, s46, s24
	s_mov_b32 s49, m0
	s_mov_b32 m0, s47
	s_nop 0
	global_load_lds_dwordx4 v[190:191], off
	s_mov_b32 m0, s49
	s_add_i32 s46, s46, s27
	s_mov_b32 s47, m0
	s_mov_b32 m0, s46
	s_nop 0
	global_load_lds_dwordx4 v[198:199], off
	s_mov_b32 m0, s47
.LBB0_216:
	v_add_u32_e32 v96, s48, v205
	ds_read_b128 v[112:115], v96
	ds_read_b128 v[144:147], v96 offset:512
	ds_read_b128 v[148:151], v96 offset:2048
	ds_read_b128 v[152:155], v96 offset:2560
	ds_read_b128 v[156:159], v96 offset:4096
	ds_read_b128 v[160:163], v96 offset:4608
	ds_read_b128 v[164:167], v96 offset:6144
	ds_read_b128 v[168:171], v96 offset:6656
	s_xor_b64 s[40:41], s[40:41], -1
	s_waitcnt lgkmcnt(7)
	v_mfma_f32_32x32x16_bf16 v[96:111], v[112:115], v[128:131], v[80:95]
	v_mov_b64_e32 v[126:127], v[94:95]
	v_mov_b64_e32 v[124:125], v[92:93]
	v_mov_b64_e32 v[122:123], v[90:91]
	v_mov_b64_e32 v[120:121], v[88:89]
	v_mov_b64_e32 v[118:119], v[86:87]
	v_mov_b64_e32 v[116:117], v[84:85]
	v_mov_b64_e32 v[114:115], v[82:83]
	v_mov_b64_e32 v[112:113], v[80:81]
	s_waitcnt lgkmcnt(5)
	v_mfma_f32_32x32x16_bf16 v[96:111], v[148:151], v[132:135], v[96:111]
	v_add_u32_e32 v224, s48, v207
	v_mfma_f32_32x32x16_bf16 v[112:127], v[144:147], v[128:131], v[112:127]
	s_waitcnt lgkmcnt(4)
	v_mfma_f32_32x32x16_bf16 v[112:127], v[152:155], v[132:135], v[112:127]
	s_waitcnt lgkmcnt(3)
	v_mfma_f32_32x32x16_bf16 v[96:111], v[156:159], v[136:139], v[96:111]
	s_waitcnt lgkmcnt(2)
	v_mfma_f32_32x32x16_bf16 v[112:127], v[160:163], v[136:139], v[112:127]
	s_waitcnt lgkmcnt(1)
	v_mfma_f32_32x32x16_bf16 v[96:111], v[164:167], v[140:143], v[96:111]
	s_waitcnt lgkmcnt(0)
	v_mfma_f32_32x32x16_bf16 v[112:127], v[168:171], v[140:143], v[112:127]
	ds_read_b64_tr_b16 v[172:173], v224 offset:49152
	ds_read_b64_tr_b16 v[174:175], v224 offset:49664
	ds_read_b64_tr_b16 v[164:165], v224 offset:50176
	ds_read_b64_tr_b16 v[166:167], v224 offset:50688
	ds_read_b64_tr_b16 v[156:157], v224 offset:51200
	ds_read_b64_tr_b16 v[158:159], v224 offset:51712
	ds_read_b64_tr_b16 v[144:145], v224 offset:52224
	ds_read_b64_tr_b16 v[146:147], v224 offset:52736
	ds_read_b64_tr_b16 v[168:169], v224 offset:53248
	ds_read_b64_tr_b16 v[170:171], v224 offset:53760
	ds_read_b64_tr_b16 v[160:161], v224 offset:54272
	ds_read_b64_tr_b16 v[162:163], v224 offset:54784
	ds_read_b64_tr_b16 v[152:153], v224 offset:55296
	ds_read_b64_tr_b16 v[154:155], v224 offset:55808
	ds_read_b64_tr_b16 v[148:149], v224 offset:56320
	ds_read_b64_tr_b16 v[150:151], v224 offset:56832
	v_max_f32_e32 v225, v112, v112
	v_max_f32_e32 v242, v96, v96
	v_max_f32_e32 v225, v242, v225
	v_max3_f32 v225, v225, v97, v113
	v_max3_f32 v225, v225, v98, v114
	v_max3_f32 v225, v225, v99, v115
	v_max3_f32 v225, v225, v100, v116
	v_max3_f32 v225, v225, v101, v117
	v_max3_f32 v225, v225, v102, v118
	v_max3_f32 v225, v225, v103, v119
	v_max3_f32 v225, v225, v104, v120
	v_max3_f32 v225, v225, v105, v121
	v_max3_f32 v225, v225, v106, v122
	v_max3_f32 v225, v225, v107, v123
	v_max3_f32 v225, v225, v108, v124
	v_max3_f32 v225, v225, v109, v125
	v_max3_f32 v225, v225, v110, v126
	v_max3_f32 v225, v225, v111, v127
	v_mov_b32_e32 v242, v225
	s_nop 1
	v_permlane32_swap_b32_e32 v225, v242
	v_max_f32_e32 v242, v242, v242
	v_max_f32_e32 v225, v225, v225
	v_cndmask_b32_e64 v243, 0, 1, s[40:41]
	v_cmp_ne_u32_e64 s[46:47], 1, v243
	s_andn2_b64 vcc, exec, s[40:41]
	v_max_f32_e32 v249, v225, v242
	s_cbranch_vccnz .LBB0_229
	v_cmp_lt_f32_e32 vcc, s90, v249
	s_mov_b64 s[48:49], 0
	s_mov_b64 s[40:41], 0
	s_cbranch_vccz .LBB0_219
	v_max_f32_e32 v225, v249, v249
	v_max_f32_e32 v225, 0, v225
	s_mov_b64 s[40:41], -1

; #define LAS __attribute__((address_space(3)))
; template <int DQK, int DV, bool BAND>
; DI void attn_unit(const AttnArgs& a, LAS unsigned char* lds, int tid) {
;     ...
;                 if (!first) {
;                     const float alpha = __builtin_amdgcn_exp2f(-delta);
;                     if (hi == 0) scr[r32] = alpha;
; #pragma unroll
;                     for (int g = 0; g < 4; ++g) { const f32x4 al = *(const LAS f32x4*)(scr + 8 * g + 4 * hi);
;                         lacc[4 * g] *= al.x; lacc[4 * g + 1] *= al.y; lacc[4 * g + 2] *= al.z; lacc[4 * g + 3] *= al.w;
; #pragma unroll
;                         for (int d = 0; d < NDB; ++d) { o[d][4 * g] *= al.x; o[d][4 * g + 1] *= al.y; o[d][4 * g + 2] *= al.z; o[d][4 * g + 3] *= al.w; } }
.LBB0_221:
	s_andn2_b64 vcc, exec, s[40:41]
	s_cbranch_vccnz .LBB0_227
	s_and_b64 vcc, exec, s[46:47]
	s_cbranch_vccnz .LBB0_226
	v_exp_f32_e64 v80, -v225
	s_and_saveexec_b64 s[40:41], s[44:45]
	ds_write_b32 v185, v80
	s_or_b64 exec, exec, s[40:41]
	v_mul_f32_e32 v64, v64, v80
	v_mul_f32_e32 v65, v65, v80
	ds_read_b128 v[80:83], v187 offset:96
	ds_read_b128 v[84:87], v187 offset:64
	ds_read_b128 v[88:91], v187 offset:32
	ds_read_b128 v[92:95], v187
	s_waitcnt lgkmcnt(3)
	v_pk_mul_f32 v[14:15], v[14:15], v[82:83]
	s_waitcnt lgkmcnt(2)
	v_pk_mul_f32 v[10:11], v[10:11], v[86:87]
	s_waitcnt lgkmcnt(1)
	v_pk_mul_f32 v[6:7], v[6:7], v[90:91]
	s_waitcnt lgkmcnt(0)
	v_pk_mul_f32 v[2:3], v[2:3], v[94:95]
	v_pk_mul_f32 v[12:13], v[12:13], v[80:81]
	v_pk_mul_f32 v[8:9], v[8:9], v[84:85]
	v_pk_mul_f32 v[4:5], v[4:5], v[88:89]
	v_pk_mul_f32 v[0:1], v[0:1], v[92:93]
	v_pk_mul_f32 v[62:63], v[62:63], v[82:83]
	v_pk_mul_f32 v[58:59], v[58:59], v[86:87]
	v_pk_mul_f32 v[54:55], v[54:55], v[90:91]
	v_pk_mul_f32 v[50:51], v[50:51], v[94:95]
	v_pk_mul_f32 v[60:61], v[60:61], v[80:81]
	v_pk_mul_f32 v[56:57], v[56:57], v[84:85]
	v_pk_mul_f32 v[52:53], v[52:53], v[88:89]
	v_pk_mul_f32 v[48:49], v[48:49], v[92:93]
	v_pk_mul_f32 v[46:47], v[46:47], v[82:83]
	v_pk_mul_f32 v[42:43], v[42:43], v[86:87]
	v_pk_mul_f32 v[38:39], v[38:39], v[90:91]
	v_pk_mul_f32 v[34:35], v[34:35], v[94:95]
	v_pk_mul_f32 v[44:45], v[44:45], v[80:81]
	v_pk_mul_f32 v[40:41], v[40:41], v[84:85]
	v_pk_mul_f32 v[36:37], v[36:37], v[88:89]
	v_pk_mul_f32 v[32:33], v[32:33], v[92:93]
	v_pk_mul_f32 v[30:31], v[30:31], v[82:83]
	v_pk_mul_f32 v[26:27], v[26:27], v[86:87]
	v_pk_mul_f32 v[22:23], v[22:23], v[90:91]
	v_pk_mul_f32 v[18:19], v[18:19], v[94:95]
	v_pk_mul_f32 v[28:29], v[28:29], v[80:81]
	v_pk_mul_f32 v[24:25], v[24:25], v[84:85]
	v_pk_mul_f32 v[20:21], v[20:21], v[88:89]
	v_pk_mul_f32 v[16:17], v[16:17], v[92:93]

; template <int DQK, int DV, bool BAND>
; DI void attn_unit(const AttnArgs& a, LAS unsigned char* lds, int tid) {
;     ...
;             for (int r = 0; r < 16; ++r) { p0[r] = __builtin_amdgcn_exp2f(p0[r]); p1[r] = __builtin_amdgcn_exp2f(p1[r]); }
;             { u32x4 w;
;               w.x = pk2(p0[0], p0[1]); w.y = pk2(p0[2], p0[3]); w.z = pk2(p0[4], p0[5]); w.w = pk2(p0[6], p0[7]); pa[0] = __builtin_bit_cast(bf16x8, w);
;               w.x = pk2(p0[8], p0[9]); w.y = pk2(p0[10], p0[11]); w.z = pk2(p0[12], p0[13]); w.w = pk2(p0[14], p0[15]); pa[1] = __builtin_bit_cast(bf16x8, w);
;               w.x = pk2(p1[0], p1[1]); w.y = pk2(p1[2], p1[3]); w.z = pk2(p1[4], p1[5]); w.w = pk2(p1[6], p1[7]); pa[2] = __builtin_bit_cast(bf16x8, w);
;               w.x = pk2(p1[8], p1[9]); w.y = pk2(p1[10], p1[11]); w.z = pk2(p1[12], p1[13]); w.w = pk2(p1[14], p1[15]); pa[3] = __builtin_bit_cast(bf16x8, w); }
;             if (DQK > 96) { AT_PV(vcur); } else {
;                 if (!VPRE) { const LAS unsigned char* vp_ = lds + VBUF + vcur + ((lane >> 4) & 1) * 32 + (lane & 3) * 8 + (4 * hi + ((lane & 15) >> 2)) * 64;
; #pragma unroll
;                     for (int d = 0; d < 2; ++d)
; #pragma unroll
;                         for (int ks = 0; ks < 4; ++ks) { vlo[d * 4 + ks] = vtr(vp_ + d * 4096 + ks * 1024); vhi[d * 4 + ks] = vtr(vp_ + d * 4096 + ks * 1024 + 512); }
;                     __builtin_amdgcn_sched_barrier(0); }
; #pragma unroll
;                 for (int ks = 0; ks < 4; ++ks) {
; #pragma unroll
;                     for (int d = 0; d < 2; ++d) { const s16x4 lo = vlo[d * 4 + ks], hh = vhi[d * 4 + ks];
;                         const bf16x8 vf = (bf16x8){lo[0], lo[1], lo[2], lo[3], hh[0], hh[1], hh[2], hh[3]}; o[d] = MFMA32(pa[ks], vf, o[d]); }
;                     lacc = MFMA32(pa[ks], ones, lacc); }
;                 if (NDB > 2) {
;                     const LAS unsigned char* vp_ = lds + VBUF + vcur + ((lane >> 4) & 1) * 32 + (lane & 3) * 8 + (4 * hi + ((lane & 15) >> 2)) * 64;
; #pragma unroll
;                     for (int d = 2; d < NDB; ++d)
; #pragma unroll
;                         for (int ks = 0; ks < 4; ++ks) { vlo[(d - 2) * 4 + ks] = vtr(vp_ + d * 4096 + ks * 1024); vhi[(d - 2) * 4 + ks] = vtr(vp_ + d * 4096 + ks * 1024 + 512); }
;                     __builtin_amdgcn_sched_barrier(0);
; #pragma unroll
;                     for (int ks = 0; ks < 4; ++ks)
.LBB0_227:
	v_exp_f32_e32 v96, v96
	v_exp_f32_e32 v97, v97
	v_exp_f32_e32 v98, v98
	v_exp_f32_e32 v99, v99
	v_exp_f32_e32 v100, v100
	v_exp_f32_e32 v101, v101
	v_exp_f32_e32 v102, v102
	v_exp_f32_e32 v103, v103
	v_exp_f32_e32 v225, v108
	v_exp_f32_e32 v242, v109
	v_exp_f32_e32 v243, v110
	v_exp_f32_e32 v249, v111
	v_cvt_pk_bf16_f32 v108, v96, v97
	v_cvt_pk_bf16_f32 v109, v98, v99
	v_cvt_pk_bf16_f32 v110, v100, v101
	v_cvt_pk_bf16_f32 v111, v102, v103
	v_exp_f32_e32 v104, v104
	v_exp_f32_e32 v105, v105
	v_exp_f32_e32 v106, v106
	v_exp_f32_e32 v107, v107
	s_waitcnt lgkmcnt(14)
	v_mfma_f32_32x32x16_bf16 v[0:15], v[108:111], v[172:175], v[0:15]
	v_add_f32_e32 v64, v64, v104
	v_add_f32_e32 v65, v65, v105
	v_cvt_pk_bf16_f32 v104, v104, v105
	v_exp_f32_e32 v112, v112
	v_add_f32_e32 v64, v64, v106
	v_add_f32_e32 v65, v65, v107
	v_cvt_pk_bf16_f32 v105, v106, v107
	v_cvt_pk_bf16_f32 v106, v225, v242
	v_cvt_pk_bf16_f32 v107, v243, v249
	v_exp_f32_e32 v113, v113
	v_exp_f32_e32 v114, v114
	s_waitcnt lgkmcnt(6)
	v_mfma_f32_32x32x16_bf16 v[48:63], v[108:111], v[168:171], v[48:63]
	v_add_f32_e32 v64, v64, v96
	v_add_f32_e32 v65, v65, v97
	v_add_f32_e32 v64, v64, v98
	v_add_f32_e32 v65, v65, v99
	v_exp_f32_e32 v115, v115
	v_exp_f32_e32 v116, v116
	v_exp_f32_e32 v117, v117
	v_exp_f32_e32 v118, v118
	v_exp_f32_e32 v119, v119
	v_add_f32_e32 v64, v64, v100
	v_add_f32_e32 v65, v65, v101
	v_add_f32_e32 v64, v64, v102
	v_add_f32_e32 v65, v65, v103
	v_cvt_pk_bf16_f32 v100, v112, v113
	v_cvt_pk_bf16_f32 v101, v114, v115
	v_mfma_f32_32x32x16_bf16 v[0:15], v[104:107], v[164:167], v[0:15]
	v_cvt_pk_bf16_f32 v102, v116, v117
	v_cvt_pk_bf16_f32 v103, v118, v119
	v_exp_f32_e32 v120, v120
	v_exp_f32_e32 v121, v121
	v_exp_f32_e32 v122, v122
	v_exp_f32_e32 v123, v123
	v_exp_f32_e32 v124, v124
	v_add_f32_e32 v64, v64, v116
	v_add_f32_e32 v65, v65, v117
	v_add_f32_e32 v64, v64, v118
	v_add_f32_e32 v65, v65, v119
	s_waitcnt lgkmcnt(4)
	v_mfma_f32_32x32x16_bf16 v[48:63], v[104:107], v[160:163], v[48:63]
	v_exp_f32_e32 v125, v125
	v_exp_f32_e32 v126, v126
	v_exp_f32_e32 v127, v127
	v_cvt_pk_bf16_f32 v96, v120, v121
	v_cvt_pk_bf16_f32 v97, v122, v123
	v_mfma_f32_32x32x16_bf16 v[0:15], v[100:103], v[156:159], v[0:15]
	v_cvt_pk_bf16_f32 v98, v124, v125
	v_cvt_pk_bf16_f32 v99, v126, v127
	v_add_f32_e32 v64, v64, v120
	v_add_f32_e32 v65, v65, v121
	v_add_f32_e32 v64, v64, v122
	v_add_f32_e32 v65, v65, v123
	s_waitcnt lgkmcnt(2)
	v_mfma_f32_32x32x16_bf16 v[48:63], v[100:103], v[152:155], v[48:63]
	v_add_f32_e32 v64, v64, v124
	v_add_f32_e32 v65, v65, v125
	v_add_f32_e32 v64, v64, v126
	v_add_f32_e32 v65, v65, v127
	v_mfma_f32_32x32x16_bf16 v[0:15], v[96:99], v[144:147], v[0:15]
	s_waitcnt lgkmcnt(0)
	v_mfma_f32_32x32x16_bf16 v[48:63], v[96:99], v[148:151], v[48:63]
	ds_read_b64_tr_b16 v[116:117], v224 offset:57344
	ds_read_b64_tr_b16 v[118:119], v224 offset:57856
	ds_read_b64_tr_b16 v[120:121], v224 offset:58368
	ds_read_b64_tr_b16 v[122:123], v224 offset:58880
	ds_read_b64_tr_b16 v[124:125], v224 offset:59392
	ds_read_b64_tr_b16 v[126:127], v224 offset:59904
	ds_read_b64_tr_b16 v[144:145], v224 offset:60416
	ds_read_b64_tr_b16 v[146:147], v224 offset:60928
	ds_read_b64_tr_b16 v[148:149], v224 offset:61440
	ds_read_b64_tr_b16 v[150:151], v224 offset:61952
	ds_read_b64_tr_b16 v[152:153], v224 offset:62464
	ds_read_b64_tr_b16 v[154:155], v224 offset:62976
	ds_read_b64_tr_b16 v[156:157], v224 offset:63488
	ds_read_b64_tr_b16 v[158:159], v224 offset:64000
	ds_read_b64_tr_b16 v[160:161], v224 offset:64512
	ds_read_b64_tr_b16 v[162:163], v224 offset:65024
	v_add_f32_e32 v64, v64, v112
	v_add_f32_e32 v65, v65, v113
	v_add_f32_e32 v64, v64, v114
	v_add_f32_e32 v65, v65, v115
	s_waitcnt lgkmcnt(14)
	v_mfma_f32_32x32x16_bf16 v[32:47], v[108:111], v[116:119], v[32:47]
	v_add_f32_e32 v64, v64, v225
	v_add_f32_e32 v65, v65, v242
	v_add_f32_e32 v64, v64, v243
	v_add_f32_e32 v65, v65, v249
	s_add_i32 s34, s34, 1
	s_add_i32 s46, s82, s34
	v_lshl_add_u64 v[190:191], v[190:191], 0, s[74:75]
	v_lshl_add_u64 v[198:199], v[198:199], 0, s[74:75]
	v_lshl_add_u64 v[200:201], v[200:201], 0, s[74:75]
	s_mov_b64 s[40:41], 0
	s_cmp_eq_u32 s46, 2
	s_waitcnt lgkmcnt(6)
	v_mfma_f32_32x32x16_bf16 v[16:31], v[108:111], v[148:151], v[16:31]
	v_mfma_f32_32x32x16_bf16 v[32:47], v[104:107], v[120:123], v[32:47]
	s_waitcnt lgkmcnt(4)
	v_mfma_f32_32x32x16_bf16 v[16:31], v[104:107], v[152:155], v[16:31]
	v_mfma_f32_32x32x16_bf16 v[32:47], v[100:103], v[124:127], v[32:47]
	s_waitcnt lgkmcnt(2)
	v_mfma_f32_32x32x16_bf16 v[16:31], v[100:103], v[156:159], v[16:31]
	v_mfma_f32_32x32x16_bf16 v[32:47], v[96:99], v[144:147], v[32:47]
	s_waitcnt lgkmcnt(0)
	v_mfma_f32_32x32x16_bf16 v[16:31], v[96:99], v[160:163], v[16:31]
	s_cbranch_scc1 .LBB0_207
	s_mov_b32 s48, s35
	s_add_i32 s35, s34, -1
	s_cmp_ge_u32 s35, s69
	s_mov_b64 s[46:47], -1
	s_cbranch_scc1 .LBB0_211
	s_branch .LBB0_212

; #define LAS __attribute__((address_space(3)))
; template <int DQK, int DV, bool BAND>
; DI void attn_unit(const AttnArgs& a, LAS unsigned char* lds, int tid) {
;     ...
;             if (t + 1 < t_hi) AT_WAITBAR(NLD); else AT_WAITBAR(0);
;             vnext = vcur == 32768 ? 0 : vcur + 16384; const int vnn = vnext == 32768 ? 0 : vnext + 16384;
;             if (t + 2 < t_hi) AT_DMA(t + 2, vnn);
;         }
;         bool active = true;
;         if (BAND) active = (64 * t + 63 >= qw - 64) && (64 * t <= qw + 95);
;         if (active) {
;             f32x16 p0, p1;
;             const LAS unsigned char* kb = lds + KBUF + vcur + hi * 1024 + r32 * 16;
; #pragma unroll
;             for (int dg = 0; dg < ND0; dg += KG) {
;                 bf16x8 kf0[KG], kf1[KG];
; #pragma unroll
;                 for (int j = 0; j < KG; ++j) if (dg + j < ND0) { kf0[j] = *(const LAS bf16x8*)(kb + (dg + j) * 2048); kf1[j] = *(const LAS bf16x8*)(kb + (dg + j) * 2048 + 512); }
;                 __builtin_amdgcn_sched_barrier(0);
; #pragma unroll
;                 for (int j = 0; j < KG; ++j) if (dg + j < ND0) {
;                     if (dg + j == 0) { p0 = MFMA32(kf0[j], qf[0], negm); p1 = MFMA32(kf1[j], qf[0], negm); }
;                     else { p0 = MFMA32(kf0[j], qf[dg + j], p0); p1 = MFMA32(kf1[j], qf[dg + j], p1); }
;                 }
;             }
;             s16x4 vlo[8], vhi[8];
;             if (VPRE) { const LAS unsigned char* vp_ = lds + VBUF + vcur + ((lane >> 4) & 1) * 32 + (lane & 3) * 8 + (4 * hi + ((lane & 15) >> 2)) * 64;
; #pragma unroll
;               for (int d = 0; d < 2; ++d)
; #pragma unroll
;                   for (int ks = 0; ks < 4; ++ks) { vlo[d * 4 + ks] = vtr(vp_ + d * 4096 + ks * 1024); vhi[d * 4 + ks] = vtr(vp_ + d * 4096 + ks * 1024 + 512); } }
;             __builtin_amdgcn_sched_barrier(0);
;             if (BAND) { const int qi = qw + r32; const int kb0 = 64 * t + 4 * hi;
; #pragma unroll
;                 for (int r = 0; r < 16; ++r) { const int kv = kb0 + (r & 3) + 8 * (r >> 2); int d = qi - kv; d = d < 0 ? -d : d; if (d > 64) p0[r] = -1e30f; int d2 = qi - kv - 32; d2 = d2 < 0 ? -d2 : d2; if (d2 > 64) p1[r] = -1e30f; } }
;             if (!a.nomax) {
;             float mx = fmaxf(p0[0], p1[0]);
; #pragma unroll
;             for (int r = 1; r < 16; ++r) mx = fmaxf(fmaxf(mx, p0[r]), p1[r]);
.LBB0_241:
	s_add_i32 s24, s26, 0x4000
	s_cmpk_lg_u32 s26, 0x8000
	s_cselect_b32 s24, s24, 0
	s_add_i32 s27, s27, 2
	s_cmp_ge_u32 s27, s69
	s_cbranch_scc1 .LBB0_243
	s_add_i32 s27, s24, 0x4000
	s_cmpk_lg_u32 s24, 0x8000
	s_cselect_b32 s27, s27, 0
	s_add_i32 s34, s17, s27
	s_mov_b32 s35, m0
	s_mov_b32 m0, s34
	s_nop 0
	global_load_lds_dwordx4 v[158:159], off
	s_mov_b32 m0, s35
	s_add_i32 s27, s18, s27
	s_mov_b32 s34, m0
	s_mov_b32 m0, s27
	s_nop 0
	global_load_lds_dwordx4 v[156:157], off
	s_mov_b32 m0, s34
.LBB0_243:
	v_add_u32_e32 v64, s26, v162
	ds_read_b128 v[80:83], v64
	ds_read_b128 v[112:115], v64 offset:512
	ds_read_b128 v[116:119], v64 offset:2048
	ds_read_b128 v[120:123], v64 offset:2560
	ds_read_b128 v[124:127], v64 offset:4096
	ds_read_b128 v[128:131], v64 offset:4608
	ds_read_b128 v[132:135], v64 offset:6144
	ds_read_b128 v[136:139], v64 offset:6656
	s_waitcnt lgkmcnt(7)
	v_mfma_f32_32x32x16_bf16 v[64:79], v[80:83], v[96:99], v[48:63]
	v_mov_b64_e32 v[94:95], v[62:63]
	v_mov_b64_e32 v[92:93], v[60:61]
	v_mov_b64_e32 v[90:91], v[58:59]
	v_mov_b64_e32 v[88:89], v[56:57]
	v_mov_b64_e32 v[86:87], v[54:55]
	v_mov_b64_e32 v[84:85], v[52:53]
	v_mov_b64_e32 v[82:83], v[50:51]
	v_mov_b64_e32 v[80:81], v[48:49]
	s_waitcnt lgkmcnt(5)
	v_mfma_f32_32x32x16_bf16 v[64:79], v[116:119], v[100:103], v[64:79]
	v_add_u32_e32 v118, s26, v164
	v_mfma_f32_32x32x16_bf16 v[80:95], v[112:115], v[96:99], v[80:95]
	s_waitcnt lgkmcnt(4)
	v_mfma_f32_32x32x16_bf16 v[80:95], v[120:123], v[100:103], v[80:95]
	s_waitcnt lgkmcnt(3)
	v_mfma_f32_32x32x16_bf16 v[64:79], v[124:127], v[104:107], v[64:79]
	s_waitcnt lgkmcnt(2)
	v_mfma_f32_32x32x16_bf16 v[80:95], v[128:131], v[104:107], v[80:95]
	s_waitcnt lgkmcnt(1)
	v_mfma_f32_32x32x16_bf16 v[64:79], v[132:135], v[108:111], v[64:79]
	s_waitcnt lgkmcnt(0)
	v_mfma_f32_32x32x16_bf16 v[80:95], v[136:139], v[108:111], v[80:95]
	ds_read_b64_tr_b16 v[140:141], v118 offset:49152
	ds_read_b64_tr_b16 v[142:143], v118 offset:49664
	ds_read_b64_tr_b16 v[132:133], v118 offset:50176
	ds_read_b64_tr_b16 v[134:135], v118 offset:50688
	ds_read_b64_tr_b16 v[124:125], v118 offset:51200
	ds_read_b64_tr_b16 v[126:127], v118 offset:51712
	ds_read_b64_tr_b16 v[112:113], v118 offset:52224
	ds_read_b64_tr_b16 v[114:115], v118 offset:52736
	ds_read_b64_tr_b16 v[136:137], v118 offset:53248
	ds_read_b64_tr_b16 v[138:139], v118 offset:53760
	ds_read_b64_tr_b16 v[128:129], v118 offset:54272
	ds_read_b64_tr_b16 v[130:131], v118 offset:54784
	ds_read_b64_tr_b16 v[120:121], v118 offset:55296
	ds_read_b64_tr_b16 v[122:123], v118 offset:55808
	ds_read_b64_tr_b16 v[116:117], v118 offset:56320
	ds_read_b64_tr_b16 v[118:119], v118 offset:56832
	s_and_saveexec_b64 s[50:51], s[44:45]
	s_cbranch_execz .LBB0_257
	v_max_f32_e32 v174, v80, v80
	v_max_f32_e32 v175, v64, v64
	v_max_f32_e32 v174, v175, v174
	v_max3_f32 v174, v174, v65, v81
	v_max3_f32 v174, v174, v66, v82
	v_max3_f32 v174, v174, v67, v83
	v_max3_f32 v174, v174, v68, v84
	v_max3_f32 v174, v174, v69, v85
	v_max3_f32 v174, v174, v70, v86
	v_max3_f32 v174, v174, v71, v87
	v_max3_f32 v174, v174, v72, v88
	v_max3_f32 v174, v174, v73, v89
	v_max3_f32 v174, v174, v74, v90
	v_max3_f32 v174, v174, v75, v91
	v_max3_f32 v174, v174, v76, v92
	v_max3_f32 v174, v174, v77, v93
	v_max3_f32 v174, v174, v78, v94
	v_max3_f32 v174, v174, v79, v95
	v_mov_b32_e32 v175, v174
	s_nop 1
	v_permlane32_swap_b32_e32 v174, v175
	v_max_f32_e32 v175, v175, v175
	v_max_f32_e32 v174, v174, v174
	s_xor_b64 s[54:55], s[48:49], -1
	v_max_f32_e32 v175, v174, v175
	s_mov_b64 s[52:53], 0
	s_and_saveexec_b64 s[26:27], s[54:55]
	s_xor_b64 s[40:41], exec, s[26:27]
	s_cbranch_execnz .LBB0_247
	s_andn2_saveexec_b64 s[40:41], s[40:41]
	s_cbranch_execnz .LBB0_250
